# attention loop back-edge rotation: row-sum update adds and loop exit test moved in front of the per-tile barrier
# speedup vs baseline: 1.0007x; 1.0007x over previous
.LBB0_1017:
	v_add_f32_e32 v229, v227, v228
	v_add_f32_e32 v195, v229, v195
	s_waitcnt lgkmcnt(0)
	s_barrier
	ds_read_b128 v[120:123], v179 offset:34816
	ds_read_b128 v[196:199], v179 offset:34848
	ds_read_b128 v[200:203], v179 offset:34880
	ds_read_b128 v[204:207], v179 offset:34912
	v_max_f32_e32 v124, v80, v64
	s_add_i32 s8, s7, 2
	s_min_u32 s9, s8, s6
	s_lshl_b32 s9, s9, 17
	buffer_load_dwordx4 v[112:115], v191, s[0:3], s9 offen
	buffer_load_dwordx4 v[116:119], v192, s[0:3], s9 offen
	v_max3_f32 v125, v88, v72, v89
	v_max3_f32 v124, v124, v81, v65
	v_max3_f32 v125, v125, v73, v90
	v_max3_f32 v124, v124, v82, v66
	v_max3_f32 v125, v125, v74, v91
	v_max3_f32 v124, v124, v83, v67
	v_max3_f32 v125, v125, v75, v92
	v_max3_f32 v124, v124, v84, v68
	v_max3_f32 v125, v125, v76, v93
	v_max3_f32 v124, v124, v85, v69
	v_max3_f32 v125, v125, v77, v94
	v_max3_f32 v124, v124, v86, v70
	v_max3_f32 v125, v125, v78, v95
	v_max3_f32 v124, v124, v87, v71
	v_max3_f32 v124, v125, v79, v124
	s_waitcnt lgkmcnt(3)
	v_mfma_f32_32x32x16_bf16 v[48:63], v[120:123], v[156:159], v[48:63]
	v_mov_b32_e32 v125, v124
	ds_read_b128 v[208:211], v179 offset:39424
	s_nop 1
	v_permlane32_swap_b32_e32 v125, v124
	v_max_f32_e32 v193, v124, v125
	s_min_u32 s9, s7, s6
	s_lshl_b32 s9, s9, 7
	buffer_load_dwordx4 v[124:127], v177, s[24:27], s9 offen
	buffer_load_dwordx4 v[120:123], v178, s[24:27], s9 offen
	v_sub_f32_e32 v216, v193, v194
	s_waitcnt lgkmcnt(3)
	v_mfma_f32_32x32x16_bf16 v[48:63], v[196:199], v[152:155], v[48:63]
	v_mul_f32_e32 v196, 0x3e38aa3b, v216
	v_cmp_ge_f32_e32 vcc, s72, v196
	ds_read_b128 v[212:215], v179 offset:39456
	s_cmp_eq_u64 vcc, exec
	v_max_f32_e32 v220, v194, v193
	s_cselect_b64 vcc, -1, 0
	v_cndmask_b32_e32 v193, v220, v194, vcc
	v_mul_f32_e32 v238, 0xbe38aa3b, v193
	v_fmamk_f32 v80, v80, 0x3e38aa3b, v238
	v_fmamk_f32 v81, v81, 0x3e38aa3b, v238
	s_waitcnt lgkmcnt(3)
	v_mfma_f32_32x32x16_bf16 v[48:63], v[200:203], v[148:151], v[48:63]
	ds_read_b128 v[216:219], v179 offset:39488
	v_exp_f32_e32 v196, v80
	v_exp_f32_e32 v197, v81
	v_fmamk_f32 v198, v82, 0x3e38aa3b, v238
	v_fmamk_f32 v199, v83, 0x3e38aa3b, v238
	s_waitcnt lgkmcnt(3)
	v_mfma_f32_32x32x16_bf16 v[48:63], v[204:207], v[144:147], v[48:63]
	ds_read_b128 v[80:83], v179 offset:39520
	v_exp_f32_e32 v198, v198
	v_exp_f32_e32 v199, v199
	v_add_f32_e32 v202, 0, v196
	v_add_f32_e32 v203, 0, v197
	v_fmamk_f32 v84, v84, 0x3e38aa3b, v238
	v_fmamk_f32 v85, v85, 0x3e38aa3b, v238
	s_waitcnt lgkmcnt(3)
	v_mfma_f32_32x32x16_bf16 v[32:47], v[208:211], v[156:159], v[32:47]
	ds_read_b128 v[222:225], v179 offset:44032
	v_exp_f32_e32 v200, v84
	v_exp_f32_e32 v201, v85
	v_add_f32_e32 v204, v198, v202
	v_add_f32_e32 v205, v199, v203
	v_fmamk_f32 v202, v86, 0x3e38aa3b, v238
	v_fmamk_f32 v203, v87, 0x3e38aa3b, v238
	s_waitcnt lgkmcnt(3)
	v_mfma_f32_32x32x16_bf16 v[32:47], v[212:215], v[152:155], v[32:47]
	ds_read_b128 v[84:87], v179 offset:44064
	v_exp_f32_e32 v202, v202
	v_exp_f32_e32 v203, v203
	v_add_f32_e32 v206, v200, v204
	v_add_f32_e32 v207, v201, v205
	v_fmamk_f32 v88, v88, 0x3e38aa3b, v238
	v_fmamk_f32 v89, v89, 0x3e38aa3b, v238
	s_waitcnt lgkmcnt(3)
	v_mfma_f32_32x32x16_bf16 v[32:47], v[216:219], v[148:151], v[32:47]
	ds_read_b128 v[226:229], v179 offset:44096
	v_exp_f32_e32 v204, v88
	v_exp_f32_e32 v205, v89
	v_add_f32_e32 v208, v202, v206
	v_add_f32_e32 v209, v203, v207
	v_fmamk_f32 v206, v90, 0x3e38aa3b, v238
	v_fmamk_f32 v207, v91, 0x3e38aa3b, v238
	s_waitcnt lgkmcnt(3)
	v_mfma_f32_32x32x16_bf16 v[32:47], v[80:83], v[144:147], v[32:47]
	ds_read_b128 v[88:91], v179 offset:44128
	v_exp_f32_e32 v206, v206
	v_exp_f32_e32 v207, v207
	v_add_f32_e32 v210, v204, v208
	v_add_f32_e32 v211, v205, v209
	v_fmamk_f32 v92, v92, 0x3e38aa3b, v238
	v_fmamk_f32 v93, v93, 0x3e38aa3b, v238
	s_waitcnt lgkmcnt(3)
	v_mfma_f32_32x32x16_bf16 v[16:31], v[222:225], v[156:159], v[16:31]
	ds_read_b128 v[80:83], v179 offset:48640
	v_exp_f32_e32 v208, v92
	v_exp_f32_e32 v209, v93
	v_add_f32_e32 v212, v206, v210
	v_add_f32_e32 v213, v207, v211
	v_fmamk_f32 v210, v94, 0x3e38aa3b, v238
	v_fmamk_f32 v211, v95, 0x3e38aa3b, v238
	s_waitcnt lgkmcnt(3)
	v_mfma_f32_32x32x16_bf16 v[16:31], v[84:87], v[152:155], v[16:31]
	ds_read_b128 v[92:95], v179 offset:48672
	v_exp_f32_e32 v210, v210
	v_exp_f32_e32 v211, v211
	v_add_f32_e32 v214, v208, v212
	v_add_f32_e32 v215, v209, v213
	v_fmamk_f32 v64, v64, 0x3e38aa3b, v238
	v_fmamk_f32 v65, v65, 0x3e38aa3b, v238
	s_waitcnt lgkmcnt(3)
	v_mfma_f32_32x32x16_bf16 v[16:31], v[226:229], v[148:151], v[16:31]
	ds_read_b128 v[84:87], v179 offset:48704
	v_exp_f32_e32 v212, v64
	v_exp_f32_e32 v213, v65
	v_add_f32_e32 v216, v210, v214
	v_add_f32_e32 v217, v211, v215
	v_fmamk_f32 v214, v66, 0x3e38aa3b, v238
	v_fmamk_f32 v215, v67, 0x3e38aa3b, v238
	s_waitcnt lgkmcnt(3)
	v_mfma_f32_32x32x16_bf16 v[16:31], v[88:91], v[144:147], v[16:31]
	ds_read_b128 v[64:67], v179 offset:48736
	v_exp_f32_e32 v214, v214
	v_exp_f32_e32 v215, v215
	v_add_f32_e32 v218, v212, v216
	v_add_f32_e32 v219, v213, v217
	v_fmamk_f32 v68, v68, 0x3e38aa3b, v238
	v_fmamk_f32 v69, v69, 0x3e38aa3b, v238
	s_waitcnt lgkmcnt(3)
	v_mfma_f32_32x32x16_bf16 v[0:15], v[80:83], v[156:159], v[0:15]
	ds_read_b128 v[88:91], v187
	v_exp_f32_e32 v216, v68
	v_exp_f32_e32 v217, v69
	v_add_f32_e32 v221, v214, v218
	v_add_f32_e32 v222, v215, v219
	v_fmamk_f32 v80, v70, 0x3e38aa3b, v238
	v_fmamk_f32 v81, v71, 0x3e38aa3b, v238
	s_waitcnt lgkmcnt(3)
	v_mfma_f32_32x32x16_bf16 v[0:15], v[92:95], v[152:155], v[0:15]
	ds_read_b128 v[68:71], v187 offset:8704
	v_exp_f32_e32 v218, v80
	v_exp_f32_e32 v219, v81
	v_add_f32_e32 v80, v216, v221
	v_add_f32_e32 v81, v217, v222
	v_fmamk_f32 v72, v72, 0x3e38aa3b, v238
	v_fmamk_f32 v73, v73, 0x3e38aa3b, v238
	s_waitcnt lgkmcnt(3)
	v_mfma_f32_32x32x16_bf16 v[0:15], v[84:87], v[148:151], v[0:15]
	ds_read_b128 v[244:247], v187 offset:32
	v_exp_f32_e32 v221, v72
	v_exp_f32_e32 v222, v73
	v_add_f32_e32 v72, v218, v80
	v_add_f32_e32 v73, v219, v81
	v_fmamk_f32 v74, v74, 0x3e38aa3b, v238
	v_fmamk_f32 v75, v75, 0x3e38aa3b, v238
	s_waitcnt lgkmcnt(3)
	v_mfma_f32_32x32x16_bf16 v[0:15], v[64:67], v[144:147], v[0:15]
	ds_read_b128 v[248:251], v187 offset:8736
	v_exp_f32_e32 v223, v74
	v_exp_f32_e32 v224, v75
	v_add_f32_e32 v72, v221, v72
	v_add_f32_e32 v73, v222, v73
	v_fmamk_f32 v64, v76, 0x3e38aa3b, v238
	v_fmamk_f32 v65, v77, 0x3e38aa3b, v238
	s_waitcnt lgkmcnt(3)
	v_mfma_f32_32x32x16_bf16 v[80:95], v[88:91], v[96:99], 0
	ds_read_b128 v[252:255], v187 offset:64
	v_exp_f32_e32 v146, v64
	v_exp_f32_e32 v147, v65
	v_add_f32_e32 v64, v223, v72
	v_add_f32_e32 v65, v224, v73
	v_fmamk_f32 v66, v78, 0x3e38aa3b, v238
	v_fmac_f32_e32 v238, 0x3e38aa3b, v79
	v_exp_f32_e32 v225, v66
	v_add_f32_e32 v227, v146, v64
	v_add_f32_e32 v229, v147, v65
	s_waitcnt lgkmcnt(3)
	v_mfma_f32_32x32x16_bf16 v[64:79], v[68:71], v[96:99], 0
	ds_read_b128 v[234:237], v187 offset:8768
	v_exp_f32_e32 v226, v238
	s_waitcnt lgkmcnt(3)
	v_mfma_f32_32x32x16_bf16 v[80:95], v[244:247], v[100:103], v[80:95]
	ds_read_b128 v[238:241], v187 offset:96
	v_cvt_pk_bf16_f32 v156, v196, v197
	v_cvt_pk_bf16_f32 v157, v198, v199
	v_add_f32_e32 v227, v225, v227
	v_add_f32_e32 v228, v226, v229
	s_waitcnt lgkmcnt(3)
	v_mfma_f32_32x32x16_bf16 v[64:79], v[248:251], v[100:103], v[64:79]
	ds_read_b128 v[244:247], v187 offset:8800
	v_cvt_pk_bf16_f32 v158, v200, v201
	v_cvt_pk_bf16_f32 v159, v202, v203
	s_waitcnt lgkmcnt(3)
	v_mfma_f32_32x32x16_bf16 v[80:95], v[252:255], v[104:107], v[80:95]
	v_cvt_pk_bf16_f32 v152, v204, v205
	v_cvt_pk_bf16_f32 v153, v206, v207
	s_waitcnt vmcnt(7)
	ds_write_b128 v186, v[128:131] offset:17408
	s_waitcnt vmcnt(6)
	ds_write_b128 v186, v[132:135] offset:26112
	v_add_u32_e32 v128, 0xd000, v188
	s_waitcnt vmcnt(5)
	ds_write2_b64 v128, v[140:141], v[142:143] offset1:2
	v_add_u32_e32 v128, 0xf000, v188
	s_waitcnt vmcnt(4)
	ds_write2_b64 v128, v[136:137], v[138:139] offset0:128 offset1:130
	s_waitcnt lgkmcnt(6)
	v_mfma_f32_32x32x16_bf16 v[64:79], v[234:237], v[104:107], v[64:79]
	v_cvt_pk_bf16_f32 v154, v208, v209
	v_cvt_pk_bf16_f32 v155, v210, v211
	s_waitcnt lgkmcnt(5)
	v_mfma_f32_32x32x16_bf16 v[80:95], v[238:241], v[108:111], v[80:95]
	v_cvt_pk_bf16_f32 v148, v212, v213
	v_cvt_pk_bf16_f32 v149, v214, v215
	s_waitcnt lgkmcnt(4)
	v_mfma_f32_32x32x16_bf16 v[64:79], v[244:247], v[108:111], v[64:79]
	v_cvt_pk_bf16_f32 v150, v216, v217
	v_cvt_pk_bf16_f32 v151, v218, v219
	v_cvt_pk_bf16_f32 v144, v221, v222
	v_cvt_pk_bf16_f32 v145, v223, v224
	v_cvt_pk_bf16_f32 v146, v146, v147
	v_cvt_pk_bf16_f32 v147, v225, v226
	s_cbranch_vccnz .LBB0_1019
	v_sub_f32_e32 v128, v194, v220
	v_mul_f32_e32 v128, 0x3e38aa3b, v128
	v_exp_f32_e32 v128, v128
	s_nop 0
	v_pk_mul_f32 v[62:63], v[128:129], v[62:63] op_sel_hi:[0,1]
	v_pk_mul_f32 v[60:61], v[128:129], v[60:61] op_sel_hi:[0,1]
	v_pk_mul_f32 v[58:59], v[128:129], v[58:59] op_sel_hi:[0,1]
	v_pk_mul_f32 v[56:57], v[128:129], v[56:57] op_sel_hi:[0,1]
	v_pk_mul_f32 v[54:55], v[128:129], v[54:55] op_sel_hi:[0,1]
	v_pk_mul_f32 v[52:53], v[128:129], v[52:53] op_sel_hi:[0,1]
	v_pk_mul_f32 v[50:51], v[128:129], v[50:51] op_sel_hi:[0,1]
	v_pk_mul_f32 v[48:49], v[128:129], v[48:49] op_sel_hi:[0,1]
	v_pk_mul_f32 v[46:47], v[128:129], v[46:47] op_sel_hi:[0,1]
	v_pk_mul_f32 v[44:45], v[128:129], v[44:45] op_sel_hi:[0,1]
	v_pk_mul_f32 v[42:43], v[128:129], v[42:43] op_sel_hi:[0,1]
	v_pk_mul_f32 v[40:41], v[128:129], v[40:41] op_sel_hi:[0,1]
	v_pk_mul_f32 v[38:39], v[128:129], v[38:39] op_sel_hi:[0,1]
	v_pk_mul_f32 v[36:37], v[128:129], v[36:37] op_sel_hi:[0,1]
	v_pk_mul_f32 v[34:35], v[128:129], v[34:35] op_sel_hi:[0,1]
	v_pk_mul_f32 v[32:33], v[128:129], v[32:33] op_sel_hi:[0,1]
	v_pk_mul_f32 v[30:31], v[128:129], v[30:31] op_sel_hi:[0,1]
	v_pk_mul_f32 v[28:29], v[128:129], v[28:29] op_sel_hi:[0,1]
	v_pk_mul_f32 v[26:27], v[128:129], v[26:27] op_sel_hi:[0,1]
	v_pk_mul_f32 v[24:25], v[128:129], v[24:25] op_sel_hi:[0,1]
	v_pk_mul_f32 v[22:23], v[128:129], v[22:23] op_sel_hi:[0,1]
	v_pk_mul_f32 v[20:21], v[128:129], v[20:21] op_sel_hi:[0,1]
	v_pk_mul_f32 v[18:19], v[128:129], v[18:19] op_sel_hi:[0,1]
	v_pk_mul_f32 v[16:17], v[128:129], v[16:17] op_sel_hi:[0,1]
	v_pk_mul_f32 v[14:15], v[128:129], v[14:15] op_sel_hi:[0,1]
	v_pk_mul_f32 v[12:13], v[128:129], v[12:13] op_sel_hi:[0,1]
	v_pk_mul_f32 v[10:11], v[128:129], v[10:11] op_sel_hi:[0,1]
	v_pk_mul_f32 v[8:9], v[128:129], v[8:9] op_sel_hi:[0,1]
	v_pk_mul_f32 v[6:7], v[128:129], v[6:7] op_sel_hi:[0,1]
	v_pk_mul_f32 v[4:5], v[128:129], v[4:5] op_sel_hi:[0,1]
	v_pk_mul_f32 v[2:3], v[128:129], v[2:3] op_sel_hi:[0,1]
	v_pk_mul_f32 v[0:1], v[128:129], v[0:1] op_sel_hi:[0,1]
	v_mul_f32_e32 v195, v195, v128
.LBB0_1019:
	v_add_f32_e32 v229, v227, v228
	v_add_f32_e32 v195, v229, v195
	s_cmp_ge_u32 s7, s4
	s_waitcnt lgkmcnt(0)
	s_barrier
	s_cbranch_scc1 .LBB0_1021
	s_mov_b32 s7, s8
	s_branch .LBB0_1015
